# MLA loop: absolute running K/V tile pointers (7 fewer VALU per tile) and one static s_setprio 1 for the trailing (younger) half-workgroup during the MLA units
# speedup vs baseline: 1.0436x; 1.0120x over previous
; DEV int ltid() { int t = threadIdx.x; asm volatile("" : "+v"(t)); return t; }
; DEV int v_st(int k, int c) { const int kk = (k & ~0xC) | ((k & 4) << 1) | ((k & 8) >> 1); return ((kk >> 3) * 4 + (c >> 5)) * 512 + ((kk & 7) * 32 + (c & 31)) * 2; }
; DEV int v_rd_base(int lane) { return ((lane & 3) << 3) | (((lane >> 2) & 3) << 6) | (((lane >> 4) & 1) << 5) | (((lane >> 5) & 1) << 8); }
; template <int DQK, bool WIN, bool TWO>
; DEV void attn_unit(const bf16_t* Qb, int ldq, const bf16_t* __restrict__ Kh, int ldk, const bf16_t* __restrict__ Vh, int ldv,
;                    bf16_t* Ob, int ldo, int kbeg, int NT, int q0, float sink, const float SCALE, char* lds) {
;   using CF = ACfg<DQK>;
;   constexpr int KROW = CF::KROW, KT = CF::KT, NKP = CF::NKP, PPR = CF::PPR, SHM_V = 16384;
;   const float C = SCALE * 1.4426950408889634f, thr_raw = 8.f / SCALE;
;   const int tid = ltid(), wid = tid >> 6, lane = tid & 63, r32 = lane & 31, hi = lane >> 5;
;   char* V_lds = lds; char* K_lds = lds + 2 * SHM_V;
;   float* wsf = (float*)(lds + 2 * SHM_V + 2 * KT) + wid * 64; float* li_l = wsf; float* al_l = wsf + 32;
;   float m_reg = -1e30f, l_reg = 0;
;   f32x16 o[4];
; #pragma unroll
;   for (int d = 0; d < 4; ++d)
; #pragma unroll
;     for (int r = 0; r < 16; ++r) o[d][r] = 0.f;
;   constexpr int NQR = TWO ? 4 : DQK / 16;
;   bf16x8 qr[NQR];
;   const bf16_t* Qw = Qb + (size_t)(wid * 32 + r32) * ldq + hi * 8;
;   char* qlds = lds + 2 * SHM_V + 2 * KT + 2048 + wid * 8192 + lane * 16;
; #pragma unroll
;   for (int d0 = 0; d0 < NQR; ++d0) qr[d0] = *(const bf16x8*)(Qw + d0 * 16);
; #pragma unroll
;   for (int d0 = NQR; d0 < DQK / 16; ++d0) *(bf16x8*)(qlds + (d0 - NQR) * 1024) = *(const bf16x8*)(Qw + d0 * 16);
;   const int sr = tid >> 4, sc = (tid & 15) * 8, vst0 = v_st(sr, sc), vst1 = v_st(32 + sr, sc);
;   const int vb0 = (int)(uintptr_t)V_lds + v_rd_base(lane);
;   const unsigned voff = (unsigned)(sr * ldv + sc) * 2u, vstep = (unsigned)ldv * 64u;
;   unsigned koff[NKP]; int klds[NKP];
; #pragma unroll
;   for (int i = 0; i < NKP; ++i) { const int p = tid + i * NTHR; const int kr = p / PPR, kc = (p % PPR) * 8; koff[i] = (unsigned)(kr * ldk + kc) * 2u; klds[i] = kr * KROW + kc * 2; }
;   const int qpos = q0 + wid * 32 + r32;
;   bf16x8 svs0, svs1, sks[NKP];
.LBB0_460:
	s_and_b32 s0, s21, 7
	s_bfe_u32 s1, s26, 0x50003
	v_readlane_b32 s2, v252, 46
	s_mul_i32 s35, s0, 0x180
	s_lshl_b32 s34, s0, 8
	s_ashr_i32 s0, s26, 8
	s_and_b32 s18, s1, s2
	v_readlane_b32 s2, v253, 50
	s_lshr_b32 s1, s1, s51
	s_lshl_b32 s0, s0, s2
	s_add_i32 s0, s1, s0
	s_ashr_i32 s1, s0, 31
	v_readlane_b32 s2, v249, 0
	s_and_b32 s24, s26, 7
	s_lshl_b64 s[2:3], s[0:1], s2
	s_lshl_b32 s0, s18, 8
	s_add_u32 s0, s2, s0
	s_addc_u32 s1, s3, 0
	s_mul_i32 s18, s1, 0xc00
	s_mul_hi_u32 s19, s0, 0xc00
	s_add_i32 s19, s19, s18
	s_mul_i32 s18, s0, 0xc00
	s_add_u32 s18, s78, s18
	s_addc_u32 s19, s79, s19
	s_mul_i32 s25, s24, 0x180
	s_add_u32 s38, s18, s25
	s_mul_i32 s18, s3, 0xc00
	s_mul_hi_u32 s40, s2, 0xc00
	s_addc_u32 s39, s19, 0
	s_add_i32 s40, s40, s18
	s_mul_i32 s41, s2, 0xc00
	v_readlane_b32 s4, v250, 0
	v_readlane_b32 s5, v250, 1
	s_add_u32 s18, s4, s41
	s_addc_u32 s19, s5, s40
	s_add_u32 s18, s18, s25
	s_addc_u32 s19, s19, 0
	s_lshl_b64 s[2:3], s[2:3], 11
	v_readlane_b32 s4, v249, 6
	v_readlane_b32 s5, v249, 7
	s_add_u32 s25, s4, s2
	s_addc_u32 s42, s5, s3
	s_lshl_b32 s27, s24, 7
	s_lshl_b32 s24, s24, 8
	v_mov_b32_e32 v2, v204
	s_add_u32 s24, s25, s24
	s_addc_u32 s25, s42, 0
	v_ashrrev_i32_e32 v3, 6, v2
	v_and_b32_e32 v175, 31, v2
	v_and_b32_e32 v0, 0x3fffffc0, v2
	s_add_i32 s42, 0, 0x14800
	v_lshlrev_b32_e32 v174, 5, v3
	v_lshl_add_u32 v173, v0, 2, s42
	v_bfe_u32 v172, v2, 5, 1
	v_or_b32_e32 v4, v174, v175
	v_mov_b64_e32 v[0:1], s[38:39]
	s_movk_i32 s4, 0xc00
	v_mad_i64_i32 v[0:1], s[38:39], v4, s4, v[0:1]
	v_lshlrev_b32_e32 v196, 4, v172
	v_lshl_add_u64 v[0:1], v[0:1], 0, v[196:197]
	global_load_dwordx4 v[140:143], v[0:1], off
	global_load_dwordx4 v[136:139], v[0:1], off offset:32
	global_load_dwordx4 v[132:135], v[0:1], off offset:64
	global_load_dwordx4 v[128:131], v[0:1], off offset:96
	global_load_dwordx4 v[124:127], v[0:1], off offset:128
	global_load_dwordx4 v[120:123], v[0:1], off offset:160
	global_load_dwordx4 v[116:119], v[0:1], off offset:192
	global_load_dwordx4 v[112:115], v[0:1], off offset:224
	global_load_dwordx4 v[108:111], v[0:1], off offset:256
	global_load_dwordx4 v[104:107], v[0:1], off offset:288
	global_load_dwordx4 v[100:103], v[0:1], off offset:320
	global_load_dwordx4 v[96:99], v[0:1], off offset:352
	v_ashrrev_i32_e32 v0, 4, v2
	v_lshlrev_b32_e32 v31, 13, v3
	v_and_b32_e32 v3, 0xfffff0, v0
	v_lshlrev_b32_e32 v4, 1, v0
	v_and_or_b32 v3, v4, 8, v3
	v_lshrrev_b32_e32 v4, 1, v0
	v_and_b32_e32 v6, 3, v0
	v_and_or_b32 v4, v4, 4, v6
	v_lshlrev_b32_e32 v38, 6, v4
	v_add_u32_e32 v4, 32, v0
	v_and_b32_e32 v6, 0xfffff0, v4
	v_lshlrev_b32_e32 v4, 1, v4
	v_lshlrev_b32_e32 v33, 3, v2
	v_and_or_b32 v4, v4, 8, v6
	v_bfe_u32 v5, v33, 5, 2
	v_lshrrev_b32_e32 v4, 1, v4
	v_or_b32_e32 v4, v4, v5
	s_mov_b32 s5, 0x2aaaaaab
	v_lshrrev_b32_e32 v3, 1, v3
	v_lshlrev_b32_e32 v39, 9, v4
	v_mul_hi_i32 v4, v2, s5
	v_or_b32_e32 v3, v3, v5
	v_lshrrev_b32_e32 v5, 31, v4
	v_ashrrev_i32_e32 v4, 2, v4
	v_add_u32_e32 v4, v4, v5
	v_mul_lo_u32 v5, v4, 24
	v_sub_u32_e32 v5, v2, v5
	v_mul_lo_u32 v6, v4, s4
	v_lshl_add_u32 v16, v5, 4, v6
	s_movk_i32 s39, 0xf590
	v_mad_u64_u32 v[20:21], s[42:43], v4, s39, v[16:17]
	v_add_u32_e32 v4, 0x200, v2
	v_mul_hi_i32 v5, v4, s5
	v_lshrrev_b32_e32 v6, 31, v5
	v_ashrrev_i32_e32 v5, 2, v5
	v_add_u32_e32 v5, v5, v6
	v_mul_lo_u32 v6, v5, 24
	v_and_b32_e32 v30, 63, v2
	v_lshlrev_b32_e32 v40, 1, v2
	v_sub_u32_e32 v4, v4, v6
	v_mul_lo_u32 v6, v5, s4
	v_add_u32_e32 v2, 0x400, v2
	s_waitcnt lgkmcnt(0)
	v_lshl_add_u32 v18, v4, 4, v6
	v_mul_hi_i32 v4, v2, s5
	v_mad_u64_u32 v[24:25], s[42:43], v5, s39, v[18:19]
	v_lshrrev_b32_e32 v5, 31, v4
	v_ashrrev_i32_e32 v4, 2, v4
	v_and_b32_e32 v1, 0x78, v33
	v_add_u32_e32 v4, v4, v5
	v_lshlrev_b32_e32 v1, 1, v1
	v_mul_lo_u32 v5, v4, 24
	v_lshlrev_b32_e32 v3, 9, v3
	v_sub_u32_e32 v2, v2, v5
	v_mul_lo_u32 v5, v4, s4
	v_and_b32_e32 v21, 48, v1
	v_lshl_or_b32 v28, v0, 11, v1
	v_lshl_add_u32 v22, v2, 4, v5
	v_or3_b32 v25, v3, v38, v21
	global_load_dwordx4 v[0:3], v28, s[24:25]
	global_load_dwordx4 v[34:37], v22, s[18:19]
	v_mov_b32_e32 v29, v197
	v_mad_u64_u32 v[26:27], s[42:43], v4, s39, v[22:23]
	v_lshl_add_u64 v[4:5], s[24:25], 0, v[28:29]
	s_mov_b32 s4, 0x10000
	v_add_co_u32_e32 v4, vcc, s4, v4
	global_load_dwordx4 v[8:11], v16, s[18:19]
	global_load_dwordx4 v[12:15], v18, s[18:19]
	v_addc_co_u32_e32 v5, vcc, 0, v5, vcc
	global_load_dwordx4 v[4:7], v[4:5], off
	v_add_u32_e32 v179, 0, v25
	s_add_i32 s38, 0, 0x15000
	s_waitcnt vmcnt(0)
	s_movk_i32 s18, 0x118
	v_lshlrev_b32_e32 v32, 4, v30
	s_cmp_lg_u32 0, -1
	v_and_b32_e32 v27, 0xc0, v32
	v_or3_b32 v21, v39, v38, v21
	v_add_u32_e32 v180, 0, v21
	v_add_u32_e32 v182, 0, v20
	v_add_u32_e32 v183, 0, v24
	v_mov_b32_e32 v17, v197
	v_mov_b32_e32 v19, v197
	v_mov_b32_e32 v23, v197
	v_add_u32_e32 v184, 0, v26
	v_add3_u32 v181, s38, v31, v32
	v_cmp_gt_u32_e64 s[38:39], 32, v30
	s_mov_b32 s24, 0
	s_mov_b32 s101, 0
	s_bitcmp1_b32 s100, 0
	s_cbranch_scc0 .Lmla_noprio
	s_setprio 1
; DEV int v_st(int k, int c) { const int kk = (k & ~0xC) | ((k & 4) << 1) | ((k & 8) >> 1); return ((kk >> 3) * 4 + (c >> 5)) * 512 + ((kk & 7) * 32 + (c & 31)) * 2; }
; DEV int v_rd_base(int lane) { return ((lane & 3) << 3) | (((lane >> 2) & 3) << 6) | (((lane >> 4) & 1) << 5) | (((lane >> 5) & 1) << 8); }
; template <int DQK, bool WIN, bool TWO>
; DEV void attn_unit(const bf16_t* Qb, int ldq, const bf16_t* __restrict__ Kh, int ldk, const bf16_t* __restrict__ Vh, int ldv,
;                    bf16_t* Ob, int ldo, int kbeg, int NT, int q0, float sink, const float SCALE, char* lds) {
;     ...
;   const int sr = tid >> 4, sc = (tid & 15) * 8, vst0 = v_st(sr, sc), vst1 = v_st(32 + sr, sc);
;   const int vb0 = (int)(uintptr_t)V_lds + v_rd_base(lane);
;   const unsigned voff = (unsigned)(sr * ldv + sc) * 2u, vstep = (unsigned)ldv * 64u;
;   unsigned koff[NKP]; int klds[NKP];
; #pragma unroll
;   for (int i = 0; i < NKP; ++i) { const int p = tid + i * NTHR; const int kr = p / PPR, kc = (p % PPR) * 8; koff[i] = (unsigned)(kr * ldk + kc) * 2u; klds[i] = kr * KROW + kc * 2; }
.Lmla_noprio:
	v_lshl_add_u32 v176, v175, 2, v173
	v_mov_b32_e32 v187, 0
	v_mov_b32_e32 v178, 0
	v_mov_b32_e32 v226, 0
	v_mov_b32_e32 v227, 0
	v_mov_b32_e32 v228, 0
	v_mov_b32_e32 v229, 0
	v_mov_b32_e32 v230, 0
	v_mov_b32_e32 v231, 0
	v_mov_b32_e32 v232, 0
	v_mov_b32_e32 v233, 0
	v_mov_b32_e32 v234, 0
	v_mov_b32_e32 v235, 0
	v_mov_b32_e32 v236, 0
	v_mov_b32_e32 v237, 0
	v_mov_b32_e32 v238, 0
	v_mov_b32_e32 v239, 0
	v_mov_b32_e32 v240, 0
	v_mov_b32_e32 v241, 0
	s_waitcnt vmcnt(0)
	ds_write_b128 v179, v[0:3]
	v_and_b32_e32 v0, 32, v40
	v_and_or_b32 v0, v33, s18, v0
	s_movk_i32 s18, 0x190
	v_mad_u32_u24 v185, v175, s18, 0
	s_cselect_b32 s18, 0, 0
	v_add3_u32 v177, v27, s18, v0
	s_add_u32 s18, s41, s35
	s_addc_u32 s19, s40, 0
	s_add_u32 s18, s18, 0x2c934000
	s_addc_u32 s19, s19, 0
	s_or_b32 s2, s2, s34
	v_lshl_add_u64 v[164:165], s[18:19], 0, v[16:17]
	ds_write_b128 v180, v[4:7]
	ds_write_b128 v182, v[8:11] offset:32768
	ds_write_b128 v183, v[12:15] offset:32768
	v_mov_b32_e32 v14, v197
	v_mov_b32_e32 v15, v197
	ds_write_b128 v184, v[34:37] offset:32768
	v_lshl_add_u64 v[166:167], s[18:19], 0, v[18:19]
	v_lshl_add_u64 v[168:169], s[18:19], 0, v[22:23]
	v_lshl_add_u64 v[170:171], s[2:3], 0, v[28:29]
	v_lshl_add_u64 v[164:165], s[64:65], 0, v[164:165]
	v_lshl_add_u64 v[166:167], s[64:65], 0, v[166:167]
	v_lshl_add_u64 v[168:169], s[64:65], 0, v[168:169]
	v_lshl_add_u64 v[170:171], s[64:65], 0, v[170:171]
	s_mov_b64 s[2:3], 0x32924000
	v_lshl_add_u64 v[246:247], s[2:3], 0, v[170:171]
	s_mov_b64 s[2:3], 0x32934000
	v_lshl_add_u64 v[170:171], s[2:3], 0, v[170:171]
	v_mov_b32_e32 v0, v197
	v_mov_b32_e32 v1, v197
	v_mov_b32_e32 v2, v197
	v_mov_b32_e32 v3, v197
	v_mov_b32_e32 v4, v197
	v_mov_b32_e32 v5, v197
	v_mov_b32_e32 v6, v197
	v_mov_b32_e32 v7, v197
	v_mov_b32_e32 v8, v197
	v_mov_b32_e32 v9, v197
	v_mov_b32_e32 v10, v197
	v_mov_b32_e32 v11, v197
	v_mov_b32_e32 v12, v197
	v_mov_b32_e32 v13, v197
	v_mov_b64_e32 v[62:63], v[14:15]
	v_mov_b64_e32 v[46:47], v[14:15]
	v_mov_b64_e32 v[30:31], v[14:15]
	v_add_u32_e32 v186, v185, v196
	v_mov_b64_e32 v[60:61], v[12:13]
	v_mov_b64_e32 v[58:59], v[10:11]
	v_mov_b64_e32 v[56:57], v[8:9]
	v_mov_b64_e32 v[54:55], v[6:7]
	v_mov_b64_e32 v[52:53], v[4:5]
	v_mov_b64_e32 v[50:51], v[2:3]
	v_mov_b64_e32 v[48:49], v[0:1]
	v_mov_b64_e32 v[44:45], v[12:13]
	v_mov_b64_e32 v[42:43], v[10:11]
	v_mov_b64_e32 v[40:41], v[8:9]
	v_mov_b64_e32 v[38:39], v[6:7]
	v_mov_b64_e32 v[36:37], v[4:5]
	v_mov_b64_e32 v[34:35], v[2:3]
	v_mov_b64_e32 v[32:33], v[0:1]
	v_mov_b64_e32 v[28:29], v[12:13]
	v_mov_b64_e32 v[26:27], v[10:11]
	v_mov_b64_e32 v[24:25], v[8:9]
	v_mov_b64_e32 v[22:23], v[6:7]
	v_mov_b64_e32 v[20:21], v[4:5]
	v_mov_b64_e32 v[18:19], v[2:3]
	v_mov_b64_e32 v[16:17], v[0:1]
	s_waitcnt lgkmcnt(0)
	s_barrier
.LBB0_461:
	s_and_b32 s18, s24, 1
	s_mul_i32 s2, s18, 0x6400
	v_add_u32_e32 v202, s2, v186
	ds_read_b128 v[188:191], v202 offset:32768
	ds_read_b128 v[198:201], v202 offset:45568
	ds_read_b128 v[214:217], v202 offset:32800
	ds_read_b128 v[218:221], v202 offset:45600
	ds_read_b128 v[222:225], v202 offset:32832
	ds_read_b128 v[242:245], v202 offset:45632
	global_load_dwordx4 v[144:147], v[246:247], off
	global_load_dwordx4 v[148:151], v[170:171], off
	global_load_dwordx4 v[152:155], v[164:165], off
	global_load_dwordx4 v[156:159], v[166:167], off
	global_load_dwordx4 v[160:163], v[168:169], off
	s_waitcnt lgkmcnt(4)
	v_mfma_f32_32x32x16_bf16 v[80:95], v[188:191], v[140:143], v[226:241]
	v_mfma_f32_32x32x16_bf16 v[64:79], v[198:201], v[140:143], v[226:241]
	ds_read_b128 v[188:191], v202 offset:32864
	ds_read_b128 v[198:201], v202 offset:45664
	s_waitcnt lgkmcnt(4)
	v_mfma_f32_32x32x16_bf16 v[80:95], v[214:217], v[136:139], v[80:95]
	v_mfma_f32_32x32x16_bf16 v[64:79], v[218:221], v[136:139], v[64:79]
	ds_read_b128 v[214:217], v202 offset:32896
	ds_read_b128 v[218:221], v202 offset:45696
	s_waitcnt lgkmcnt(4)
	v_mfma_f32_32x32x16_bf16 v[80:95], v[222:225], v[132:135], v[80:95]
	v_mfma_f32_32x32x16_bf16 v[64:79], v[242:245], v[132:135], v[64:79]
	ds_read_b128 v[222:225], v202 offset:32928
	ds_read_b128 v[242:245], v202 offset:45728
	s_waitcnt lgkmcnt(4)
	v_mfma_f32_32x32x16_bf16 v[80:95], v[188:191], v[128:131], v[80:95]
	v_mfma_f32_32x32x16_bf16 v[64:79], v[198:201], v[128:131], v[64:79]
	ds_read_b128 v[188:191], v202 offset:32960
	ds_read_b128 v[198:201], v202 offset:45760
	s_waitcnt lgkmcnt(4)
	v_mfma_f32_32x32x16_bf16 v[80:95], v[214:217], v[124:127], v[80:95]
	v_mfma_f32_32x32x16_bf16 v[64:79], v[218:221], v[124:127], v[64:79]
	ds_read_b128 v[214:217], v202 offset:32992
	ds_read_b128 v[218:221], v202 offset:45792
	s_waitcnt lgkmcnt(4)
	v_mfma_f32_32x32x16_bf16 v[80:95], v[222:225], v[120:123], v[80:95]
	v_mfma_f32_32x32x16_bf16 v[64:79], v[242:245], v[120:123], v[64:79]
	ds_read_b128 v[222:225], v202 offset:33024
	ds_read_b128 v[242:245], v202 offset:45824
	s_waitcnt lgkmcnt(4)
	v_mfma_f32_32x32x16_bf16 v[80:95], v[188:191], v[116:119], v[80:95]
	v_mfma_f32_32x32x16_bf16 v[64:79], v[198:201], v[116:119], v[64:79]
	ds_read_b128 v[188:191], v202 offset:33056
	ds_read_b128 v[198:201], v202 offset:45856
	s_waitcnt lgkmcnt(4)
	v_mfma_f32_32x32x16_bf16 v[80:95], v[214:217], v[112:115], v[80:95]
	v_mfma_f32_32x32x16_bf16 v[64:79], v[218:221], v[112:115], v[64:79]
	ds_read_b128 v[214:217], v202 offset:33088
	ds_read_b128 v[218:221], v202 offset:45888
	s_waitcnt lgkmcnt(4)
	v_mfma_f32_32x32x16_bf16 v[80:95], v[222:225], v[108:111], v[80:95]
	v_mfma_f32_32x32x16_bf16 v[64:79], v[242:245], v[108:111], v[64:79]
	ds_read_b128 v[222:225], v202 offset:33120
	ds_read_b128 v[242:245], v202 offset:45920
	s_waitcnt lgkmcnt(4)
	v_mfma_f32_32x32x16_bf16 v[80:95], v[188:191], v[104:107], v[80:95]
	v_mfma_f32_32x32x16_bf16 v[64:79], v[198:201], v[104:107], v[64:79]
	s_waitcnt lgkmcnt(2)
	v_mfma_f32_32x32x16_bf16 v[80:95], v[214:217], v[100:103], v[80:95]
	v_mfma_f32_32x32x16_bf16 v[64:79], v[218:221], v[100:103], v[64:79]
	s_waitcnt lgkmcnt(0)
	v_mfma_f32_32x32x16_bf16 v[80:95], v[222:225], v[96:99], v[80:95]
	v_mfma_f32_32x32x16_bf16 v[64:79], v[242:245], v[96:99], v[64:79]
	s_waitcnt vmcnt(0)
	s_add_i32 s3, s101, 1
	s_cmp_eq_u32 s3, 3
	s_cselect_b32 s3, 0, s3
	s_lshl_b32 s2, s3, 14
	s_cmp_eq_u32 s3, 2
	s_cselect_b32 s3, 0x15000, s2
	s_xor_b32 s2, s18, 1
	s_mul_i32 s2, s2, 0x6400
	v_add_u32_e32 v198, s3, v179
	v_add_u32_e32 v199, s3, v180
	v_add_u32_e32 v200, s2, v182
	v_add_u32_e32 v201, s2, v183
	v_add_u32_e32 v202, s2, v184
	ds_write_b128 v198, v[144:147]
	ds_write_b128 v199, v[148:151]
	ds_write_b128 v200, v[152:155] offset:32768
	ds_write_b128 v201, v[156:159] offset:32768
	ds_write_b128 v202, v[160:163] offset:32768
	s_bitcmp0_b32 s100, 0
	s_cbranch_scc1 .Lmla_lead_mid
	s_waitcnt lgkmcnt(0)
	s_barrier

; #define SLOAD(k0) do { const char* Vt_ = (const char*)(Vh + (size_t)(k0) * ldv); const char* Kt_ = (const char*)(Kh + (size_t)(k0) * ldk); \
;     svs0 = *(const bf16x8*)(Vt_ + voff); svs1 = *(const bf16x8*)(Vt_ + vstep + voff); \
;     _Pragma("unroll") for (int i_ = 0; i_ < NKP; ++i_) sks[i_] = *(const bf16x8*)(Kt_ + koff[i_]); } while (0)
; template <bool SPLIT = true> DEV void pv_d0(f32x16* o, int vb, bf16x8 pa0, bf16x8 pa1, bf16x8 pa2, bf16x8 pa3) {
;   pv_one<0, SPLIT>(o[0], vb, pa0, pa1, pa2, pa3); pv_one<1, SPLIT>(o[1], vb, pa0, pa1, pa2, pa3); pv_one<2, SPLIT>(o[2], vb, pa0, pa1, pa2, pa3); pv_one<3, SPLIT>(o[3], vb, pa0, pa1, pa2, pa3);
; }
; template <int DQK, bool WIN, bool TWO>
; DEV void attn_unit(const bf16_t* Qb, int ldq, const bf16_t* __restrict__ Kh, int ldk, const bf16_t* __restrict__ Vh, int ldv,
;                    bf16_t* Ob, int ldo, int kbeg, int NT, int q0, float sink, const float SCALE, char* lds) {
;     ...
;     if (j + 1 < NT) SLOAD(kbeg + (j + 1) * 64);
.Lmla_ok:
	s_bitset0_b32 s100, 2
	v_fmac_f32_e32 v144, v187, v188
	s_add_i32 s24, s24, 1
	s_lshl_b32 s2, s101, 14
	s_cmp_eq_u32 s101, 2
	s_cselect_b32 s2, 0x15000, s2
	v_add_u32_e32 v145, s2, v177
	ds_read_b64_tr_b16 v[80:81], v145 offset:0
	ds_read_b64_tr_b16 v[82:83], v145 offset:0x800
	ds_read_b64_tr_b16 v[84:85], v145 offset:0x1000
	ds_read_b64_tr_b16 v[86:87], v145 offset:0x1800
	ds_read_b64_tr_b16 v[88:89], v145 offset:0x2000
	ds_read_b64_tr_b16 v[90:91], v145 offset:0x2800
	ds_read_b64_tr_b16 v[92:93], v145 offset:0x3000
	ds_read_b64_tr_b16 v[94:95], v145 offset:0x3800
	s_waitcnt lgkmcnt(0)
	s_nop 0
	v_mfma_f32_32x32x16_bf16 v[0:15], v[68:71], v[80:83], v[0:15]
	ds_read_b64_tr_b16 v[80:81], v145 offset:0x200
	ds_read_b64_tr_b16 v[82:83], v145 offset:0xa00
	v_mfma_f32_32x32x16_bf16 v[0:15], v[72:75], v[84:87], v[0:15]
	ds_read_b64_tr_b16 v[84:85], v145 offset:0x1200
	ds_read_b64_tr_b16 v[86:87], v145 offset:0x1a00
	v_mfma_f32_32x32x16_bf16 v[0:15], v[76:79], v[88:91], v[0:15]
	ds_read_b64_tr_b16 v[88:89], v145 offset:0x2200
	ds_read_b64_tr_b16 v[90:91], v145 offset:0x2a00
	v_mfma_f32_32x32x16_bf16 v[0:15], v[64:67], v[92:95], v[0:15]
	ds_read_b64_tr_b16 v[92:93], v145 offset:0x3200
	ds_read_b64_tr_b16 v[94:95], v145 offset:0x3a00
	s_waitcnt lgkmcnt(0)
	v_mfma_f32_32x32x16_bf16 v[48:63], v[68:71], v[80:83], v[48:63]
	ds_read_b64_tr_b16 v[80:81], v145 offset:0x400
	ds_read_b64_tr_b16 v[82:83], v145 offset:0xc00
	v_mfma_f32_32x32x16_bf16 v[48:63], v[72:75], v[84:87], v[48:63]
	ds_read_b64_tr_b16 v[84:85], v145 offset:0x1400
	ds_read_b64_tr_b16 v[86:87], v145 offset:0x1c00
	v_mfma_f32_32x32x16_bf16 v[48:63], v[76:79], v[88:91], v[48:63]
	ds_read_b64_tr_b16 v[88:89], v145 offset:0x2400
	ds_read_b64_tr_b16 v[90:91], v145 offset:0x2c00
	v_mfma_f32_32x32x16_bf16 v[48:63], v[64:67], v[92:95], v[48:63]
	ds_read_b64_tr_b16 v[92:93], v145 offset:0x3400
	ds_read_b64_tr_b16 v[94:95], v145 offset:0x3c00
	s_waitcnt lgkmcnt(0)
	v_mfma_f32_32x32x16_bf16 v[32:47], v[68:71], v[80:83], v[32:47]
	ds_read_b64_tr_b16 v[80:81], v145 offset:0x600
	ds_read_b64_tr_b16 v[82:83], v145 offset:0xe00
	v_mfma_f32_32x32x16_bf16 v[32:47], v[72:75], v[84:87], v[32:47]
	ds_read_b64_tr_b16 v[84:85], v145 offset:0x1600
	ds_read_b64_tr_b16 v[86:87], v145 offset:0x1e00
	v_mfma_f32_32x32x16_bf16 v[32:47], v[76:79], v[88:91], v[32:47]
	ds_read_b64_tr_b16 v[88:89], v145 offset:0x2600
	ds_read_b64_tr_b16 v[90:91], v145 offset:0x2e00
	v_mfma_f32_32x32x16_bf16 v[32:47], v[64:67], v[92:95], v[32:47]
	ds_read_b64_tr_b16 v[92:93], v145 offset:0x3600
	ds_read_b64_tr_b16 v[94:95], v145 offset:0x3e00
	s_waitcnt lgkmcnt(0)
	v_mfma_f32_32x32x16_bf16 v[16:31], v[68:71], v[80:83], v[16:31]
	s_mov_b64 s[2:3], 0x20000
	v_lshl_add_u64 v[164:165], v[164:165], 0, s[62:63]
	v_lshl_add_u64 v[166:167], v[166:167], 0, s[62:63]
	v_lshl_add_u64 v[168:169], v[168:169], 0, s[62:63]
	v_lshl_add_u64 v[170:171], v[170:171], 0, s[2:3]
	v_lshl_add_u64 v[246:247], v[246:247], 0, s[2:3]
	s_add_i32 s101, s101, 1
	s_cmp_eq_u32 s101, 3
	s_cselect_b32 s101, 0, s101
	s_waitcnt lgkmcnt(0)
	s_bitcmp1_b32 s100, 0
	s_cbranch_scc1 .Lmla_trail_end
	s_barrier

; #define SBAR() __builtin_amdgcn_sched_barrier(0)
; #define RESC(a) do { if (__any((a) < 1.f)) { if (hi == 0) al_l[r32] = (a); asm volatile("s_waitcnt lgkmcnt(0)" ::: "memory"); \
;     _Pragma("unroll") for (int d = 0; d < 4; ++d) _Pragma("unroll") for (int r = 0; r < 16; ++r) o[d][r] *= al_l[crow(r, hi)]; } } while (0)
; template <int DQK, int NQR>
; DEV void qkt(f32x16& p0, f32x16& p1, const char* Ks, const bf16x8* qr, const char* qlds_, int r32, int hi) {
;   constexpr int KROW = ACfg<DQK>::KROW;
;   unsigned qa = (unsigned)(uintptr_t)qlds_; asm volatile("" : "+v"(qa));
;   const __attribute__((address_space(3))) char* qlds = (const __attribute__((address_space(3))) char*)qa;
; #pragma unroll
;   for (int r = 0; r < 16; ++r) { p0[r] = 0.f; p1[r] = 0.f; }
; #pragma unroll
;   for (int d0 = 0; d0 < DQK / 16; ++d0) {
;     const int cb = (d0 * 16 + hi * 8) * 2;
;     bf16x8 b0 = *reinterpret_cast<const bf16x8*>(Ks + r32 * KROW + cb);
;     bf16x8 b1 = *reinterpret_cast<const bf16x8*>(Ks + (32 + r32) * KROW + cb);
;     bf16x8 q;
;     if (d0 < NQR) q = qr[d0 < NQR ? d0 : 0]; else q = *reinterpret_cast<const __attribute__((address_space(3))) bf16x8*>(qlds + (d0 - NQR) * 1024);
;     p0 = __builtin_amdgcn_mfma_f32_32x32x16_bf16(b0, q, p0, 0, 0, 0);
;     p1 = __builtin_amdgcn_mfma_f32_32x32x16_bf16(b1, q, p1, 0, 0, 0);
;     if (NQR < DQK / 16 && (d0 & 3) == 3) SBAR();
;   }
; }
; template <int DQK, bool WIN, bool TWO>
; DEV void attn_unit(const bf16_t* Qb, int ldq, const bf16_t* __restrict__ Kh, int ldk, const bf16_t* __restrict__ Vh, int ldv,
;                    bf16_t* Ob, int ldo, int kbeg, int NT, int q0, float sink, const float SCALE, char* lds) {
;     ...
;     SBAR(); qkt<DQK, NQR>(pA0, pA1, K_lds + bf * KT, qr, qlds, r32, hi);
;     partialSM<WIN>(pA0, pA1, m_reg, mnA, alA, C, thr_raw, KDIFF(j));
;     RESC(alA);
.LBB0_471:
	s_setprio 0
	s_and_b32 s18, s20, 1
	s_mul_i32 s2, s18, 0x6400
	v_add3_u32 v145, v185, s2, v196
	ds_read_b128 v[64:67], v145 offset:32768
	s_waitcnt lgkmcnt(0)
	v_mfma_f32_32x32x16_bf16 v[80:95], v[64:67], v[140:143], 0
	ds_read_b128 v[64:67], v145 offset:45568
	s_waitcnt lgkmcnt(0)
	v_mfma_f32_32x32x16_bf16 v[64:79], v[64:67], v[140:143], 0
	ds_read_b128 v[140:143], v145 offset:32800
	s_waitcnt lgkmcnt(0)
	v_mfma_f32_32x32x16_bf16 v[80:95], v[140:143], v[136:139], v[80:95]
	ds_read_b128 v[140:143], v145 offset:45600
	s_waitcnt lgkmcnt(0)
	v_mfma_f32_32x32x16_bf16 v[64:79], v[140:143], v[136:139], v[64:79]
	ds_read_b128 v[136:139], v145 offset:32832
	s_waitcnt lgkmcnt(0)
	v_mfma_f32_32x32x16_bf16 v[80:95], v[136:139], v[132:135], v[80:95]
	ds_read_b128 v[136:139], v145 offset:45632
	s_waitcnt lgkmcnt(0)
	v_mfma_f32_32x32x16_bf16 v[64:79], v[136:139], v[132:135], v[64:79]
	ds_read_b128 v[132:135], v145 offset:32864
	s_waitcnt lgkmcnt(0)
	v_mfma_f32_32x32x16_bf16 v[80:95], v[132:135], v[128:131], v[80:95]
	ds_read_b128 v[132:135], v145 offset:45664
	s_waitcnt lgkmcnt(0)
	v_mfma_f32_32x32x16_bf16 v[64:79], v[132:135], v[128:131], v[64:79]
	ds_read_b128 v[128:131], v145 offset:32896
	s_waitcnt lgkmcnt(0)
	v_mfma_f32_32x32x16_bf16 v[80:95], v[128:131], v[124:127], v[80:95]
	ds_read_b128 v[128:131], v145 offset:45696
	s_waitcnt lgkmcnt(0)
	v_mfma_f32_32x32x16_bf16 v[64:79], v[128:131], v[124:127], v[64:79]
	ds_read_b128 v[124:127], v145 offset:32928
	s_waitcnt lgkmcnt(0)
	v_mfma_f32_32x32x16_bf16 v[80:95], v[124:127], v[120:123], v[80:95]
	ds_read_b128 v[124:127], v145 offset:45728
	s_waitcnt lgkmcnt(0)
	v_mfma_f32_32x32x16_bf16 v[64:79], v[124:127], v[120:123], v[64:79]
	ds_read_b128 v[120:123], v145 offset:32960
	s_waitcnt lgkmcnt(0)
	v_mfma_f32_32x32x16_bf16 v[80:95], v[120:123], v[116:119], v[80:95]
	ds_read_b128 v[120:123], v145 offset:45760
	s_waitcnt lgkmcnt(0)
	v_mfma_f32_32x32x16_bf16 v[64:79], v[120:123], v[116:119], v[64:79]
	ds_read_b128 v[116:119], v145 offset:32992
	s_waitcnt lgkmcnt(0)
	v_mfma_f32_32x32x16_bf16 v[80:95], v[116:119], v[112:115], v[80:95]
	ds_read_b128 v[116:119], v145 offset:45792
	s_waitcnt lgkmcnt(0)
	v_mfma_f32_32x32x16_bf16 v[64:79], v[116:119], v[112:115], v[64:79]
	ds_read_b128 v[112:115], v145 offset:33024
	s_waitcnt lgkmcnt(0)
	v_mfma_f32_32x32x16_bf16 v[80:95], v[112:115], v[108:111], v[80:95]
	ds_read_b128 v[112:115], v145 offset:45824
	s_waitcnt lgkmcnt(0)
	v_mfma_f32_32x32x16_bf16 v[64:79], v[112:115], v[108:111], v[64:79]
	ds_read_b128 v[108:111], v145 offset:33056
	s_waitcnt lgkmcnt(0)
	v_mfma_f32_32x32x16_bf16 v[80:95], v[108:111], v[104:107], v[80:95]
	ds_read_b128 v[108:111], v145 offset:45856
	s_waitcnt lgkmcnt(0)
	v_mfma_f32_32x32x16_bf16 v[64:79], v[108:111], v[104:107], v[64:79]
	ds_read_b128 v[104:107], v145 offset:33088
	s_waitcnt lgkmcnt(0)
	v_mfma_f32_32x32x16_bf16 v[80:95], v[104:107], v[100:103], v[80:95]
	ds_read_b128 v[104:107], v145 offset:33120
	s_waitcnt lgkmcnt(0)
	v_mfma_f32_32x32x16_bf16 v[80:95], v[104:107], v[96:99], v[80:95]
	ds_read_b128 v[104:107], v145 offset:45888
	ds_read_b128 v[108:111], v145 offset:45920
	s_waitcnt lgkmcnt(1)
	v_mfma_f32_32x32x16_bf16 v[64:79], v[104:107], v[100:103], v[64:79]
	s_nop 7
	v_max_f32_e32 v112, v81, v81
	v_max_f32_e32 v113, v80, v80
	v_max_f32_e32 v112, v113, v112
	v_max3_f32 v100, v112, v82, v83
	v_max3_f32 v100, v100, v84, v85
	v_max3_f32 v100, v100, v86, v87
	v_max3_f32 v100, v100, v88, v89
	s_waitcnt lgkmcnt(0)
	v_mfma_f32_32x32x16_bf16 v[64:79], v[108:111], v[96:99], v[64:79]
	v_max3_f32 v100, v100, v90, v91
	v_max3_f32 v100, v100, v92, v93
	v_max3_f32 v100, v100, v94, v95
	s_nop 8
	v_max3_f32 v96, v100, v64, v65
	v_max3_f32 v96, v96, v66, v67
	v_max3_f32 v96, v96, v68, v69
	v_max3_f32 v96, v96, v70, v71
	v_max3_f32 v96, v96, v72, v73
	v_max3_f32 v96, v96, v74, v75
	v_max3_f32 v96, v96, v76, v77
	v_max3_f32 v96, v96, v78, v79
	v_mov_b32_e32 v97, v96
	s_nop 1
	v_permlane32_swap_b32_e32 v96, v97
	v_max_f32_e32 v97, v97, v97
	v_max_f32_e32 v96, v96, v96
	v_max_f32_e32 v96, v96, v97
	v_max_f32_e32 v97, v178, v178
	v_max_f32_e32 v97, v97, v96
	v_sub_f32_e32 v98, v96, v178
	v_sub_f32_e32 v96, v178, v97
	v_mul_f32_e32 v96, 1.0, v96
	v_exp_f32_e32 v96, v96
	v_cmp_ge_f32_e32 vcc, 0x4138aa3b, v98
	s_cmp_eq_u64 vcc, exec
	s_cselect_b64 s[40:41], -1, 0
	v_cndmask_b32_e64 v96, v96, 1.0, s[40:41]
	v_cmp_gt_f32_e32 vcc, 1.0, v96
	s_cbranch_vccz .LBB0_475
	s_and_saveexec_b64 s[2:3], s[38:39]
	ds_write_b32 v176, v96 offset:128
	s_or_b64 exec, exec, s[2:3]
	s_waitcnt lgkmcnt(0)
	v_add_u32_e32 v110, v173, v196
	ds_read_b128 v[98:101], v110 offset:224
	ds_read_b128 v[102:105], v110 offset:192
	ds_read_b128 v[106:109], v110 offset:160
	ds_read_b128 v[110:113], v110 offset:128
	s_waitcnt lgkmcnt(3)
	v_pk_mul_f32 v[12:13], v[12:13], v[98:99]
	s_waitcnt lgkmcnt(2)
	v_pk_mul_f32 v[8:9], v[8:9], v[102:103]
	s_waitcnt lgkmcnt(1)
	v_pk_mul_f32 v[4:5], v[4:5], v[106:107]
	v_pk_mul_f32 v[14:15], v[14:15], v[100:101]
	v_pk_mul_f32 v[10:11], v[10:11], v[104:105]
	v_pk_mul_f32 v[6:7], v[6:7], v[108:109]
	s_waitcnt lgkmcnt(0)
	v_pk_mul_f32 v[2:3], v[2:3], v[112:113]
	v_pk_mul_f32 v[0:1], v[0:1], v[110:111]
	v_pk_mul_f32 v[60:61], v[60:61], v[98:99]
	v_pk_mul_f32 v[56:57], v[56:57], v[102:103]
	v_pk_mul_f32 v[52:53], v[52:53], v[106:107]
	v_pk_mul_f32 v[62:63], v[62:63], v[100:101]
	v_pk_mul_f32 v[58:59], v[58:59], v[104:105]
	v_pk_mul_f32 v[54:55], v[54:55], v[108:109]
	v_pk_mul_f32 v[50:51], v[50:51], v[112:113]
	v_pk_mul_f32 v[48:49], v[48:49], v[110:111]
	v_pk_mul_f32 v[44:45], v[44:45], v[98:99]
	v_pk_mul_f32 v[40:41], v[40:41], v[102:103]
	v_pk_mul_f32 v[36:37], v[36:37], v[106:107]
	v_pk_mul_f32 v[46:47], v[46:47], v[100:101]
	v_pk_mul_f32 v[42:43], v[42:43], v[104:105]
	v_pk_mul_f32 v[38:39], v[38:39], v[108:109]
	v_pk_mul_f32 v[34:35], v[34:35], v[112:113]
	v_pk_mul_f32 v[32:33], v[32:33], v[110:111]
	v_pk_mul_f32 v[28:29], v[28:29], v[98:99]
	v_pk_mul_f32 v[24:25], v[24:25], v[102:103]
	v_pk_mul_f32 v[20:21], v[20:21], v[106:107]
	v_pk_mul_f32 v[30:31], v[30:31], v[100:101]
	v_pk_mul_f32 v[26:27], v[26:27], v[104:105]
	v_pk_mul_f32 v[22:23], v[22:23], v[108:109]
	v_pk_mul_f32 v[18:19], v[18:19], v[112:113]
	v_pk_mul_f32 v[16:17], v[16:17], v[110:111]
